# slot fusion v5: v4 + the input copy of the pass-1 rows (x -> out rows, bf16 xb) moved from the prologue into phase 6 of (layer 0, pass 0), CU mates alternate
# speedup vs baseline: 1.0202x; 1.0062x over previous
; DEVI char* wsp(const Params& P, size_t off) { asm volatile("" : "+s"(off)); return P.ws + off; }
; DEVI int ltid() { int t = threadIdx.x; asm volatile("" : "+v"(t)); return t; }
; DEVI TokInfo tokinfo(int it) {
;   TokInfo r;
;   if (it < 8192) { r.sample = 0; r.seq = it >> 12; r.t = it & 4095; }
;   else if (it < 8448) { int q = it - 8192; r.sample = 1; r.seq = q >> 5; r.t = q & 31; }
;   else { int q = it - 8448; r.sample = 0; r.seq = 2 + (q >> 12); r.t = q & 4095; }
;   return r;
; }
; DEVI float* xrow(const Params& P, int it) {
;   TokInfo ti = tokinfo(it);
;   return ti.sample ? P.out + OUT_YS + (long)(ti.seq * 32 + ti.t) * 1024
;                    : P.out + (long)(ti.seq * 4096 + ti.t) * 1024;
; }
; DEVI void phase_xcopy(const Params& P) {
;   const int tid = ltid();
;   bfu* xb = (bfu*)wsp(P, O_XB);
;   for (int it = blockIdx.x; it < 16640; it += gridDim.x) {
;     TokInfo ti = tokinfo(it);
;     const float* src = ti.sample ? P.in[1] + (long)(ti.seq * 32 + ti.t) * 1024 : P.in[0] + (long)(ti.seq * 4096 + ti.t) * 1024;
;     float* dst = xrow(P, it);
;     int c = tid * 4;
;     float4 v = *reinterpret_cast<const float4*>(src + c);
;     *reinterpret_cast<float4*>(dst + c) = v;
;     uint2 r;
;     r.x = f2b(v.x) | ((unsigned)f2b(v.y) << 16);
;     r.y = f2b(v.z) | ((unsigned)f2b(v.w) << 16);
;     *reinterpret_cast<uint2*>(xb + (long)it * 1024 + c) = r;
;   }
; }
.Lxc_loop:
	s_mul_i32 s1, s23, 0
	s_add_i32 s1, s1, s26
	s_min_i32 s2, s1, 0x20ff
	s_sub_i32 s24, s2, 0x2000
	s_cmp_lt_u32 s24, 0x100
	s_cselect_b32 s44, s42, s40
	s_cselect_b32 s45, s43, s41
	s_cselect_b32 s27, s24, s2
	s_sub_i32 s46, s27, 0x100
	s_cmp_gt_i32 s2, 0x20ff
	s_cselect_b32 s27, s46, s27
	s_lshl_b32 s27, s27, 12
	s_add_u32 s44, s44, s27
	s_addc_u32 s45, s45, 0
	v_lshl_add_u64 v[20:21], s[44:45], 0, v[2:3]
	global_load_dwordx4 v[4:7], v[20:21], off
	s_mul_i32 s1, s23, 1
	s_add_i32 s1, s1, s26
	s_min_i32 s2, s1, 0x20ff
	s_sub_i32 s24, s2, 0x2000
	s_cmp_lt_u32 s24, 0x100
	s_cselect_b32 s44, s42, s40
	s_cselect_b32 s45, s43, s41
	s_cselect_b32 s27, s24, s2
	s_sub_i32 s46, s27, 0x100
	s_cmp_gt_i32 s2, 0x20ff
	s_cselect_b32 s27, s46, s27
	s_lshl_b32 s27, s27, 12
	s_add_u32 s44, s44, s27
	s_addc_u32 s45, s45, 0
	v_lshl_add_u64 v[20:21], s[44:45], 0, v[2:3]
	global_load_dwordx4 v[8:11], v[20:21], off
	s_mul_i32 s1, s23, 2
	s_add_i32 s1, s1, s26
	s_min_i32 s2, s1, 0x20ff
	s_sub_i32 s24, s2, 0x2000
	s_cmp_lt_u32 s24, 0x100
	s_cselect_b32 s44, s42, s40
	s_cselect_b32 s45, s43, s41
	s_cselect_b32 s27, s24, s2
	s_sub_i32 s46, s27, 0x100
	s_cmp_gt_i32 s2, 0x20ff
	s_cselect_b32 s27, s46, s27
	s_lshl_b32 s27, s27, 12
	s_add_u32 s44, s44, s27
	s_addc_u32 s45, s45, 0
	v_lshl_add_u64 v[20:21], s[44:45], 0, v[2:3]
	global_load_dwordx4 v[12:15], v[20:21], off
	s_mul_i32 s1, s23, 3
	s_add_i32 s1, s1, s26
	s_min_i32 s2, s1, 0x20ff
	s_sub_i32 s24, s2, 0x2000
	s_cmp_lt_u32 s24, 0x100
	s_cselect_b32 s44, s42, s40
	s_cselect_b32 s45, s43, s41
	s_cselect_b32 s27, s24, s2
	s_sub_i32 s46, s27, 0x100
	s_cmp_gt_i32 s2, 0x20ff
	s_cselect_b32 s27, s46, s27
	s_lshl_b32 s27, s27, 12
	s_add_u32 s44, s44, s27
	s_addc_u32 s45, s45, 0
	v_lshl_add_u64 v[20:21], s[44:45], 0, v[2:3]
	global_load_dwordx4 v[16:19], v[20:21], off
	s_mul_i32 s1, s23, 0
	s_add_i32 s1, s1, s26
	s_cmpk_ge_i32 s1, 0x2100
	s_cbranch_scc1 .Lxc_exit
	s_sub_i32 s24, s1, 0x2000
	s_cmp_lt_u32 s24, 0x100
	s_cselect_b32 s44, s33, s28
	s_cselect_b32 s45, s93, s29
	s_cselect_b32 s27, s24, s1
	s_sub_i32 s46, s27, 0x100
	s_cmp_gt_i32 s1, 0x20ff
	s_cselect_b32 s27, s46, s27
	s_lshl_b32 s27, s27, 12
	s_add_u32 s44, s44, s27
	s_addc_u32 s45, s45, 0
	v_lshl_add_u64 v[20:21], s[44:45], 0, v[2:3]
	s_ashr_i32 s47, s1, 31
	s_mov_b32 s46, s1
	s_lshl_b64 s[46:47], s[46:47], 11
	s_waitcnt vmcnt(3)
	v_and_b32_sdwa v22, v6, v95 dst_sel:DWORD dst_unused:UNUSED_PAD src0_sel:WORD_1 src1_sel:DWORD
	v_and_b32_sdwa v23, v4, v95 dst_sel:DWORD dst_unused:UNUSED_PAD src0_sel:WORD_1 src1_sel:DWORD
	global_store_dwordx4 v[20:21], v[4:7], off
	v_lshl_add_u64 v[20:21], v[0:1], 0, s[46:47]
	s_nop 0
	v_add3_u32 v4, v4, v23, s39
	v_add3_u32 v6, v6, v22, s39
	v_and_b32_sdwa v22, v7, v95 dst_sel:DWORD dst_unused:UNUSED_PAD src0_sel:WORD_1 src1_sel:DWORD
	v_and_b32_sdwa v23, v5, v95 dst_sel:DWORD dst_unused:UNUSED_PAD src0_sel:WORD_1 src1_sel:DWORD
	v_add3_u32 v7, v7, v22, s39
	v_add3_u32 v5, v5, v23, s39
	v_and_b32_e32 v7, 0xffff0000, v7
	v_and_b32_e32 v22, 0xffff0000, v5
	v_or_b32_sdwa v5, v7, v6 dst_sel:DWORD dst_unused:UNUSED_PAD src0_sel:DWORD src1_sel:WORD_1
	v_or_b32_sdwa v4, v22, v4 dst_sel:DWORD dst_unused:UNUSED_PAD src0_sel:DWORD src1_sel:WORD_1
	global_store_dwordx2 v[20:21], v[4:5], off
	s_mul_i32 s1, s23, 1
	s_add_i32 s1, s1, s26
	s_cmpk_ge_i32 s1, 0x2100
	s_cbranch_scc1 .Lxc_exit
; DEVI char* wsp(const Params& P, size_t off) { asm volatile("" : "+s"(off)); return P.ws + off; }
; DEVI int ltid() { int t = threadIdx.x; asm volatile("" : "+v"(t)); return t; }
; DEVI void phase_xcopy(const Params& P) {
;   const int tid = ltid();
;   bfu* xb = (bfu*)wsp(P, O_XB);
;   for (int it = blockIdx.x; it < 16640; it += gridDim.x) {
;     TokInfo ti = tokinfo(it);
;     const float* src = ti.sample ? P.in[1] + (long)(ti.seq * 32 + ti.t) * 1024 : P.in[0] + (long)(ti.seq * 4096 + ti.t) * 1024;
;     float* dst = xrow(P, it);
;     int c = tid * 4;
;     float4 v = *reinterpret_cast<const float4*>(src + c);
;     *reinterpret_cast<float4*>(dst + c) = v;
;     uint2 r;
;     r.x = f2b(v.x) | ((unsigned)f2b(v.y) << 16);
;     r.y = f2b(v.z) | ((unsigned)f2b(v.w) << 16);
;     *reinterpret_cast<uint2*>(xb + (long)it * 1024 + c) = r;
;   }
; }
	s_sub_i32 s24, s1, 0x2000
	s_cmp_lt_u32 s24, 0x100
	s_cselect_b32 s44, s33, s28
	s_cselect_b32 s45, s93, s29
	s_cselect_b32 s27, s24, s1
	s_sub_i32 s46, s27, 0x100
	s_cmp_gt_i32 s1, 0x20ff
	s_cselect_b32 s27, s46, s27
	s_lshl_b32 s27, s27, 12
	s_add_u32 s44, s44, s27
	s_addc_u32 s45, s45, 0
	v_lshl_add_u64 v[20:21], s[44:45], 0, v[2:3]
	s_ashr_i32 s47, s1, 31
	s_mov_b32 s46, s1
	s_lshl_b64 s[46:47], s[46:47], 11
	s_waitcnt vmcnt(4)
	v_and_b32_sdwa v22, v10, v95 dst_sel:DWORD dst_unused:UNUSED_PAD src0_sel:WORD_1 src1_sel:DWORD
	v_and_b32_sdwa v23, v8, v95 dst_sel:DWORD dst_unused:UNUSED_PAD src0_sel:WORD_1 src1_sel:DWORD
	global_store_dwordx4 v[20:21], v[8:11], off
	v_lshl_add_u64 v[20:21], v[0:1], 0, s[46:47]
	s_nop 0
	v_add3_u32 v8, v8, v23, s39
	v_add3_u32 v10, v10, v22, s39
	v_and_b32_sdwa v22, v11, v95 dst_sel:DWORD dst_unused:UNUSED_PAD src0_sel:WORD_1 src1_sel:DWORD
	v_and_b32_sdwa v23, v9, v95 dst_sel:DWORD dst_unused:UNUSED_PAD src0_sel:WORD_1 src1_sel:DWORD
	v_add3_u32 v11, v11, v22, s39
	v_add3_u32 v9, v9, v23, s39
	v_and_b32_e32 v11, 0xffff0000, v11
	v_and_b32_e32 v22, 0xffff0000, v9
	v_or_b32_sdwa v9, v11, v10 dst_sel:DWORD dst_unused:UNUSED_PAD src0_sel:DWORD src1_sel:WORD_1
	v_or_b32_sdwa v8, v22, v8 dst_sel:DWORD dst_unused:UNUSED_PAD src0_sel:DWORD src1_sel:WORD_1
	global_store_dwordx2 v[20:21], v[8:9], off
	s_mul_i32 s1, s23, 2
	s_add_i32 s1, s1, s26
	s_cmpk_ge_i32 s1, 0x2100
	s_cbranch_scc1 .Lxc_exit
	s_sub_i32 s24, s1, 0x2000
	s_cmp_lt_u32 s24, 0x100
	s_cselect_b32 s44, s33, s28
	s_cselect_b32 s45, s93, s29
	s_cselect_b32 s27, s24, s1
	s_sub_i32 s46, s27, 0x100
	s_cmp_gt_i32 s1, 0x20ff
	s_cselect_b32 s27, s46, s27
	s_lshl_b32 s27, s27, 12
	s_add_u32 s44, s44, s27
	s_addc_u32 s45, s45, 0
	v_lshl_add_u64 v[20:21], s[44:45], 0, v[2:3]
	s_ashr_i32 s47, s1, 31
	s_mov_b32 s46, s1
	s_lshl_b64 s[46:47], s[46:47], 11
	s_waitcnt vmcnt(5)
	v_and_b32_sdwa v22, v14, v95 dst_sel:DWORD dst_unused:UNUSED_PAD src0_sel:WORD_1 src1_sel:DWORD
	v_and_b32_sdwa v23, v12, v95 dst_sel:DWORD dst_unused:UNUSED_PAD src0_sel:WORD_1 src1_sel:DWORD
	global_store_dwordx4 v[20:21], v[12:15], off
	v_lshl_add_u64 v[20:21], v[0:1], 0, s[46:47]
	s_nop 0
	v_add3_u32 v12, v12, v23, s39
	v_add3_u32 v14, v14, v22, s39
	v_and_b32_sdwa v22, v15, v95 dst_sel:DWORD dst_unused:UNUSED_PAD src0_sel:WORD_1 src1_sel:DWORD
	v_and_b32_sdwa v23, v13, v95 dst_sel:DWORD dst_unused:UNUSED_PAD src0_sel:WORD_1 src1_sel:DWORD
	v_add3_u32 v15, v15, v22, s39
	v_add3_u32 v13, v13, v23, s39
	v_and_b32_e32 v15, 0xffff0000, v15
	v_and_b32_e32 v22, 0xffff0000, v13
	v_or_b32_sdwa v13, v15, v14 dst_sel:DWORD dst_unused:UNUSED_PAD src0_sel:DWORD src1_sel:WORD_1
	v_or_b32_sdwa v12, v22, v12 dst_sel:DWORD dst_unused:UNUSED_PAD src0_sel:DWORD src1_sel:WORD_1
	global_store_dwordx2 v[20:21], v[12:13], off
	s_mul_i32 s1, s23, 3
	s_add_i32 s1, s1, s26
	s_cmpk_ge_i32 s1, 0x2100
	s_cbranch_scc1 .Lxc_exit
	s_sub_i32 s24, s1, 0x2000
	s_cmp_lt_u32 s24, 0x100
	s_cselect_b32 s44, s33, s28
	s_cselect_b32 s45, s93, s29
	s_cselect_b32 s27, s24, s1
	s_sub_i32 s46, s27, 0x100
	s_cmp_gt_i32 s1, 0x20ff
	s_cselect_b32 s27, s46, s27
	s_lshl_b32 s27, s27, 12
	s_add_u32 s44, s44, s27
	s_addc_u32 s45, s45, 0
	v_lshl_add_u64 v[20:21], s[44:45], 0, v[2:3]
	s_ashr_i32 s47, s1, 31
	s_mov_b32 s46, s1
	s_lshl_b64 s[46:47], s[46:47], 11
	s_waitcnt vmcnt(6)
	v_and_b32_sdwa v22, v18, v95 dst_sel:DWORD dst_unused:UNUSED_PAD src0_sel:WORD_1 src1_sel:DWORD
	v_and_b32_sdwa v23, v16, v95 dst_sel:DWORD dst_unused:UNUSED_PAD src0_sel:WORD_1 src1_sel:DWORD
	global_store_dwordx4 v[20:21], v[16:19], off
	v_lshl_add_u64 v[20:21], v[0:1], 0, s[46:47]
	s_nop 0
	v_add3_u32 v16, v16, v23, s39
	v_add3_u32 v18, v18, v22, s39
	v_and_b32_sdwa v22, v19, v95 dst_sel:DWORD dst_unused:UNUSED_PAD src0_sel:WORD_1 src1_sel:DWORD
	v_and_b32_sdwa v23, v17, v95 dst_sel:DWORD dst_unused:UNUSED_PAD src0_sel:WORD_1 src1_sel:DWORD
	v_add3_u32 v19, v19, v22, s39
	v_add3_u32 v17, v17, v23, s39
	v_and_b32_e32 v19, 0xffff0000, v19
	v_and_b32_e32 v22, 0xffff0000, v17
	v_or_b32_sdwa v17, v19, v18 dst_sel:DWORD dst_unused:UNUSED_PAD src0_sel:DWORD src1_sel:WORD_1
	v_or_b32_sdwa v16, v22, v16 dst_sel:DWORD dst_unused:UNUSED_PAD src0_sel:DWORD src1_sel:WORD_1
	global_store_dwordx2 v[20:21], v[16:17], off
	s_lshl_b32 s1, s23, 2
	s_add_i32 s26, s26, s1
	s_cmpk_lt_i32 s26, 0x2100
	s_cbranch_scc1 .Lxc_loop

; DEVI char* wsp(const Params& P, size_t off) { asm volatile("" : "+s"(off)); return P.ws + off; }
; DEVI int ltid() { int t = threadIdx.x; asm volatile("" : "+v"(t)); return t; }
; DEVI void convert_chunk_fp8(const float* __restrict__ src, unsigned char* __restrict__ dst, float scale, int tid) {
;   int o = tid * 16;
;   uint4 r;
;   unsigned rr[4];
; #pragma unroll
;   for (int q = 0; q < 4; ++q) {
;     float4 a = *reinterpret_cast<const float4*>(src + o + q * 4);
;     int p = __builtin_amdgcn_cvt_pk_fp8_f32(a.x * scale, a.y * scale, 0, false);
;     p = __builtin_amdgcn_cvt_pk_fp8_f32(a.z * scale, a.w * scale, p, true);
;     rr[q] = (unsigned)p;
;   }
;   r = make_uint4(rr[0], rr[1], rr[2], rr[3]);
;   *reinterpret_cast<uint4*>(dst + o) = r;
; }
; DEVI void phase_xcopy(const Params& P) {
;   const int tid = ltid();
;   bfu* xb = (bfu*)wsp(P, O_XB);
;   for (int it = blockIdx.x; it < 16640; it += gridDim.x) {
;     TokInfo ti = tokinfo(it);
;     const float* src = ti.sample ? P.in[1] + (long)(ti.seq * 32 + ti.t) * 1024 : P.in[0] + (long)(ti.seq * 4096 + ti.t) * 1024;
;     float* dst = xrow(P, it);
;     int c = tid * 4;
;     float4 v = *reinterpret_cast<const float4*>(src + c);
;     *reinterpret_cast<float4*>(dst + c) = v;
;     uint2 r;
;     r.x = f2b(v.x) | ((unsigned)f2b(v.y) << 16);
;     r.y = f2b(v.z) | ((unsigned)f2b(v.w) << 16);
;     *reinterpret_cast<uint2*>(xb + (long)it * 1024 + c) = r;
;   }
; }
.Ltb_loop_a:
	s_lshl_b32 s61, s60, 14
	s_add_u32 s42, s54, s61
	s_addc_u32 s43, s55, 0
	s_add_u32 s44, s56, s61
	s_addc_u32 s45, s57, 0
	global_load_dwordx4 v[208:211], v248, s[42:43]
	global_load_dwordx4 v[212:215], v248, s[42:43] offset:16
	global_load_dwordx4 v[216:219], v248, s[42:43] offset:32
	global_load_dwordx4 v[220:223], v248, s[42:43] offset:48
	global_load_dwordx4 v[224:227], v248, s[44:45]
	global_load_dwordx4 v[228:231], v248, s[44:45] offset:16
	global_load_dwordx4 v[232:235], v248, s[44:45] offset:32
	global_load_dwordx4 v[236:239], v248, s[44:45] offset:48
	s_lshl_b32 s61, s60, 12
	s_add_u32 s58, s61, 0x2500000
	s_mov_b32 s59, 0
	v_lshl_add_u64 v[202:203], v[250:251], 0, s[58:59]
	s_add_u32 s58, s61, 0x4500000
	v_lshl_add_u64 v[204:205], v[250:251], 0, s[58:59]
	s_waitcnt vmcnt(4)
	v_mul_f32_e32 v208, 0x42800000, v208
	v_mul_f32_e32 v209, 0x42800000, v209
	v_mul_f32_e32 v210, 0x42800000, v210
	v_mul_f32_e32 v211, 0x42800000, v211
	v_mul_f32_e32 v212, 0x42800000, v212
	v_mul_f32_e32 v213, 0x42800000, v213
	v_mul_f32_e32 v214, 0x42800000, v214
	v_mul_f32_e32 v215, 0x42800000, v215
	v_mul_f32_e32 v216, 0x42800000, v216
	v_mul_f32_e32 v217, 0x42800000, v217
	v_mul_f32_e32 v218, 0x42800000, v218
	v_mul_f32_e32 v219, 0x42800000, v219
	v_mul_f32_e32 v220, 0x42800000, v220
	v_mul_f32_e32 v221, 0x42800000, v221
	v_mul_f32_e32 v222, 0x42800000, v222
	v_mul_f32_e32 v223, 0x42800000, v223
	v_mov_b32_e32 v240, v89
	v_mov_b32_e32 v241, v89
	v_mov_b32_e32 v242, v89
	v_mov_b32_e32 v243, v89
	v_cvt_pk_fp8_f32 v240, v208, v209
	v_cvt_pk_fp8_f32 v241, v212, v213
	v_cvt_pk_fp8_f32 v242, v216, v217
	v_cvt_pk_fp8_f32 v243, v220, v221
	v_cvt_pk_fp8_f32 v240, v210, v211 op_sel:[0,0,1]
	v_cvt_pk_fp8_f32 v241, v214, v215 op_sel:[0,0,1]
	v_cvt_pk_fp8_f32 v242, v218, v219 op_sel:[0,0,1]
	v_cvt_pk_fp8_f32 v243, v222, v223 op_sel:[0,0,1]
	global_store_dwordx4 v[202:203], v[240:243], off
	s_waitcnt vmcnt(1)
	v_mul_f32_e32 v224, 0x41000000, v224
	v_mul_f32_e32 v225, 0x41000000, v225
	v_mul_f32_e32 v226, 0x41000000, v226
	v_mul_f32_e32 v227, 0x41000000, v227
	v_mul_f32_e32 v228, 0x41000000, v228
	v_mul_f32_e32 v229, 0x41000000, v229
	v_mul_f32_e32 v230, 0x41000000, v230
	v_mul_f32_e32 v231, 0x41000000, v231
	v_mul_f32_e32 v232, 0x41000000, v232
	v_mul_f32_e32 v233, 0x41000000, v233
	v_mul_f32_e32 v234, 0x41000000, v234
	v_mul_f32_e32 v235, 0x41000000, v235
	v_mul_f32_e32 v236, 0x41000000, v236
	v_mul_f32_e32 v237, 0x41000000, v237
	v_mul_f32_e32 v238, 0x41000000, v238
	v_mul_f32_e32 v239, 0x41000000, v239
	v_mov_b32_e32 v244, v89
	v_mov_b32_e32 v245, v89
	v_mov_b32_e32 v246, v89
	v_mov_b32_e32 v247, v89
	v_cvt_pk_fp8_f32 v244, v224, v225
	v_cvt_pk_fp8_f32 v245, v228, v229
	v_cvt_pk_fp8_f32 v246, v232, v233
	v_cvt_pk_fp8_f32 v247, v236, v237
	v_cvt_pk_fp8_f32 v244, v226, v227 op_sel:[0,0,1]
	v_cvt_pk_fp8_f32 v245, v230, v231 op_sel:[0,0,1]
	v_cvt_pk_fp8_f32 v246, v234, v235 op_sel:[0,0,1]
	v_cvt_pk_fp8_f32 v247, v238, v239 op_sel:[0,0,1]
	global_store_dwordx4 v[204:205], v[244:247], off
	s_addk_i32 s60, 0x200
	s_cmpk_lt_u32 s60, 0x1000
	s_cbranch_scc1 .Ltb_loop_a
	s_cmp_lg_u32 s0, 0
	s_cbranch_scc1 .Ltb_skip_a
	v_readlane_b32 s44, v253, 2
	v_readlane_b32 s45, v253, 3
	v_readlane_b32 s60, v252, 32
	s_nop 4
	s_load_dwordx2 s[42:43], s[44:45], 0x0
	v_lshlrev_b32_e32 v248, 4, v93
	v_lshlrev_b32_e32 v250, 3, v93
	v_mov_b32_e32 v251, 0
	v_lshl_add_u64 v[250:251], v[64:65], 0, v[250:251]
	s_waitcnt lgkmcnt(0)
; DEVI char* wsp(const Params& P, size_t off) { asm volatile("" : "+s"(off)); return P.ws + off; }
; DEVI int ltid() { int t = threadIdx.x; asm volatile("" : "+v"(t)); return t; }
; DEVI bfu f2b(float f) {
;   unsigned u = __float_as_uint(f);
;   u += 0x7FFFu + ((u >> 16) & 1u);
;   return (bfu)(u >> 16);
; }
; DEVI void phase_xcopy(const Params& P) {
;   const int tid = ltid();
;   bfu* xb = (bfu*)wsp(P, O_XB);
;   for (int it = blockIdx.x; it < 16640; it += gridDim.x) {
;     TokInfo ti = tokinfo(it);
;     const float* src = ti.sample ? P.in[1] + (long)(ti.seq * 32 + ti.t) * 1024 : P.in[0] + (long)(ti.seq * 4096 + ti.t) * 1024;
;     float* dst = xrow(P, it);
;     int c = tid * 4;
;     float4 v = *reinterpret_cast<const float4*>(src + c);
;     *reinterpret_cast<float4*>(dst + c) = v;
;     uint2 r;
;     r.x = f2b(v.x) | ((unsigned)f2b(v.y) << 16);
;     r.y = f2b(v.z) | ((unsigned)f2b(v.w) << 16);
;     *reinterpret_cast<uint2*>(xb + (long)it * 1024 + c) = r;
;   }
; }
.Lxq_loop_a:
	s_add_i32 s61, s60, 0x2000
	s_lshl_b32 s61, s61, 12
	s_add_u32 s54, s42, s61
	s_addc_u32 s55, s43, 0
	global_load_dwordx4 v[208:211], v248, s[54:55]
	s_add_i32 s61, s60, 0x2200
	s_lshl_b32 s61, s61, 12
	s_add_u32 s54, s42, s61
	s_addc_u32 s55, s43, 0
	global_load_dwordx4 v[212:215], v248, s[54:55]
	s_add_i32 s61, s60, 0x2400
	s_lshl_b32 s61, s61, 12
	s_add_u32 s54, s42, s61
	s_addc_u32 s55, s43, 0
	global_load_dwordx4 v[216:219], v248, s[54:55]
	s_add_i32 s61, s60, 0x2600
	s_lshl_b32 s61, s61, 12
	s_add_u32 s54, s42, s61
	s_addc_u32 s55, s43, 0
	global_load_dwordx4 v[220:223], v248, s[54:55]
	s_waitcnt vmcnt(0)
	s_add_i32 s61, s60, 0x2000
	s_lshl_b32 s61, s61, 12
	s_add_u32 s56, s28, s61
	s_addc_u32 s57, s29, 0
	v_and_b32_sdwa v224, v210, v95 dst_sel:DWORD dst_unused:UNUSED_PAD src0_sel:WORD_1 src1_sel:DWORD
	v_and_b32_sdwa v225, v208, v95 dst_sel:DWORD dst_unused:UNUSED_PAD src0_sel:WORD_1 src1_sel:DWORD
	global_store_dwordx4 v248, v[208:211], s[56:57]
	s_add_i32 s58, s60, 0x2100
	s_lshl_b32 s58, s58, 11
	s_add_u32 s58, s58, 0x6502000
	s_mov_b32 s59, 0
	v_lshl_add_u64 v[202:203], v[250:251], 0, s[58:59]
	s_nop 1
	v_add3_u32 v208, v208, v225, s39
	v_add3_u32 v210, v210, v224, s39
	v_and_b32_sdwa v224, v211, v95 dst_sel:DWORD dst_unused:UNUSED_PAD src0_sel:WORD_1 src1_sel:DWORD
	v_and_b32_sdwa v225, v209, v95 dst_sel:DWORD dst_unused:UNUSED_PAD src0_sel:WORD_1 src1_sel:DWORD
	v_add3_u32 v211, v211, v224, s39
	v_add3_u32 v209, v209, v225, s39
	v_and_b32_e32 v211, 0xffff0000, v211
	v_and_b32_e32 v224, 0xffff0000, v209
	v_or_b32_sdwa v209, v211, v210 dst_sel:DWORD dst_unused:UNUSED_PAD src0_sel:DWORD src1_sel:WORD_1
	v_or_b32_sdwa v208, v224, v208 dst_sel:DWORD dst_unused:UNUSED_PAD src0_sel:DWORD src1_sel:WORD_1
	global_store_dwordx2 v[202:203], v[208:209], off
	s_add_i32 s61, s60, 0x2200
	s_lshl_b32 s61, s61, 12
	s_add_u32 s56, s28, s61
	s_addc_u32 s57, s29, 0
	v_and_b32_sdwa v224, v214, v95 dst_sel:DWORD dst_unused:UNUSED_PAD src0_sel:WORD_1 src1_sel:DWORD
	v_and_b32_sdwa v225, v212, v95 dst_sel:DWORD dst_unused:UNUSED_PAD src0_sel:WORD_1 src1_sel:DWORD
	global_store_dwordx4 v248, v[212:215], s[56:57]
	s_add_i32 s58, s60, 0x2300
	s_lshl_b32 s58, s58, 11
	s_add_u32 s58, s58, 0x6502000
	s_mov_b32 s59, 0
	v_lshl_add_u64 v[202:203], v[250:251], 0, s[58:59]
	s_nop 1
	v_add3_u32 v212, v212, v225, s39
	v_add3_u32 v214, v214, v224, s39
	v_and_b32_sdwa v224, v215, v95 dst_sel:DWORD dst_unused:UNUSED_PAD src0_sel:WORD_1 src1_sel:DWORD
	v_and_b32_sdwa v225, v213, v95 dst_sel:DWORD dst_unused:UNUSED_PAD src0_sel:WORD_1 src1_sel:DWORD
	v_add3_u32 v215, v215, v224, s39
	v_add3_u32 v213, v213, v225, s39
	v_and_b32_e32 v215, 0xffff0000, v215
	v_and_b32_e32 v224, 0xffff0000, v213
	v_or_b32_sdwa v213, v215, v214 dst_sel:DWORD dst_unused:UNUSED_PAD src0_sel:DWORD src1_sel:WORD_1
	v_or_b32_sdwa v212, v224, v212 dst_sel:DWORD dst_unused:UNUSED_PAD src0_sel:DWORD src1_sel:WORD_1
	global_store_dwordx2 v[202:203], v[212:213], off
	s_add_i32 s61, s60, 0x2400
	s_lshl_b32 s61, s61, 12
	s_add_u32 s56, s28, s61
	s_addc_u32 s57, s29, 0
	v_and_b32_sdwa v224, v218, v95 dst_sel:DWORD dst_unused:UNUSED_PAD src0_sel:WORD_1 src1_sel:DWORD
	v_and_b32_sdwa v225, v216, v95 dst_sel:DWORD dst_unused:UNUSED_PAD src0_sel:WORD_1 src1_sel:DWORD
	global_store_dwordx4 v248, v[216:219], s[56:57]
	s_add_i32 s58, s60, 0x2500
	s_lshl_b32 s58, s58, 11
	s_add_u32 s58, s58, 0x6502000
	s_mov_b32 s59, 0
	v_lshl_add_u64 v[202:203], v[250:251], 0, s[58:59]
	s_nop 1
	v_add3_u32 v216, v216, v225, s39
	v_add3_u32 v218, v218, v224, s39
	v_and_b32_sdwa v224, v219, v95 dst_sel:DWORD dst_unused:UNUSED_PAD src0_sel:WORD_1 src1_sel:DWORD
	v_and_b32_sdwa v225, v217, v95 dst_sel:DWORD dst_unused:UNUSED_PAD src0_sel:WORD_1 src1_sel:DWORD
	v_add3_u32 v219, v219, v224, s39
	v_add3_u32 v217, v217, v225, s39
	v_and_b32_e32 v219, 0xffff0000, v219
	v_and_b32_e32 v224, 0xffff0000, v217
	v_or_b32_sdwa v217, v219, v218 dst_sel:DWORD dst_unused:UNUSED_PAD src0_sel:DWORD src1_sel:WORD_1
	v_or_b32_sdwa v216, v224, v216 dst_sel:DWORD dst_unused:UNUSED_PAD src0_sel:DWORD src1_sel:WORD_1
	global_store_dwordx2 v[202:203], v[216:217], off
	s_add_i32 s61, s60, 0x2600
	s_lshl_b32 s61, s61, 12
	s_add_u32 s56, s28, s61
	s_addc_u32 s57, s29, 0
	v_and_b32_sdwa v224, v222, v95 dst_sel:DWORD dst_unused:UNUSED_PAD src0_sel:WORD_1 src1_sel:DWORD
	v_and_b32_sdwa v225, v220, v95 dst_sel:DWORD dst_unused:UNUSED_PAD src0_sel:WORD_1 src1_sel:DWORD
	global_store_dwordx4 v248, v[220:223], s[56:57]
	s_add_i32 s58, s60, 0x2700
	s_lshl_b32 s58, s58, 11
	s_add_u32 s58, s58, 0x6502000
	s_mov_b32 s59, 0
	v_lshl_add_u64 v[202:203], v[250:251], 0, s[58:59]
	s_nop 1
	v_add3_u32 v220, v220, v225, s39
	v_add3_u32 v222, v222, v224, s39
	v_and_b32_sdwa v224, v223, v95 dst_sel:DWORD dst_unused:UNUSED_PAD src0_sel:WORD_1 src1_sel:DWORD
	v_and_b32_sdwa v225, v221, v95 dst_sel:DWORD dst_unused:UNUSED_PAD src0_sel:WORD_1 src1_sel:DWORD
	v_add3_u32 v223, v223, v224, s39
	v_add3_u32 v221, v221, v225, s39
	v_and_b32_e32 v223, 0xffff0000, v223
	v_and_b32_e32 v224, 0xffff0000, v221
	v_or_b32_sdwa v221, v223, v222 dst_sel:DWORD dst_unused:UNUSED_PAD src0_sel:DWORD src1_sel:WORD_1
	v_or_b32_sdwa v220, v224, v220 dst_sel:DWORD dst_unused:UNUSED_PAD src0_sel:DWORD src1_sel:WORD_1
	global_store_dwordx2 v[202:203], v[220:221], off
	s_addk_i32 s60, 0x800
	s_cmpk_lt_u32 s60, 0x2000
	s_cbranch_scc1 .Lxq_loop_a
